# write-through sc1 16B stores in SSD/I/J phases, buffer_wbl2 dropped at those 3 grid barriers
# baseline (speedup 1.0000x reference)
.LBB0_1108:
	s_nop 0
	v_cvt_pk_bf16_f32 v56, v66, v67
	v_cvt_pk_bf16_f32 v57, v82, v83
	v_cvt_pk_bf16_f32 v58, v70, v71
	v_cvt_pk_bf16_f32 v59, v84, v85
	v_cvt_pk_bf16_f32 v60, v68, v69
	v_cvt_pk_bf16_f32 v61, v78, v79
	v_cvt_pk_bf16_f32 v62, v72, v73
	v_cvt_pk_bf16_f32 v63, v74, v75
	v_or_b32_e32 v66, 16, v164
	s_mov_b64 s[24:25], -1
	s_and_b64 vcc, exec, s[22:23]
	s_cbranch_vccz .LBB0_1110
	v_readlane_b32 s24, v254, 43
	v_readlane_b32 s25, v254, 44
	v_readlane_b32 s26, v254, 45
	v_readlane_b32 s27, v254, 46
	s_nop 4
	buffer_store_dwordx4 v[56:59], v164, s[24:27], 0 offen sc1
	buffer_store_dwordx4 v[60:63], v66, s[24:27], 0 offen sc1
	s_mov_b64 s[24:25], 0

.LBB0_1230:
	s_nop 0
	v_cvt_pk_bf16_f32 v56, v78, v79
	v_cvt_pk_bf16_f32 v57, v80, v81
	v_cvt_pk_bf16_f32 v58, v74, v75
	v_cvt_pk_bf16_f32 v59, v76, v77
	v_cvt_pk_bf16_f32 v60, v70, v71
	v_cvt_pk_bf16_f32 v61, v72, v73
	v_cvt_pk_bf16_f32 v62, v66, v67
	v_cvt_pk_bf16_f32 v63, v68, v69
	v_or_b32_e32 v66, 16, v165
	s_mov_b64 s[20:21], -1
	s_and_b64 vcc, exec, s[36:37]
	s_cbranch_vccz .LBB0_1232
	v_readlane_b32 s36, v254, 43
	v_readlane_b32 s37, v254, 44
	v_readlane_b32 s38, v254, 45
	v_readlane_b32 s39, v254, 46
	s_nop 4
	buffer_store_dwordx4 v[56:59], v165, s[36:39], 0 offen sc1
	buffer_store_dwordx4 v[60:63], v66, s[36:39], 0 offen sc1
	s_mov_b64 s[20:21], 0

.LBB0_1275:
	s_andn2_saveexec_b64 s[4:5], s[4:5]
	s_cbranch_execz .LBB0_1295
	s_mov_b64 s[4:5], exec
	s_nop 0
	s_waitcnt lgkmcnt(0)
	s_waitcnt vmcnt(0)
	v_mbcnt_lo_u32_b32 v1, s4, 0
	v_mbcnt_hi_u32_b32 v1, s5, v1
	v_cmp_eq_u32_e32 vcc, 0, v1
	s_and_saveexec_b64 s[6:7], vcc
	s_cbranch_execz .LBB0_1278
	s_bcnt1_i32_b64 s4, s[4:5]
	v_mov_b32_e32 v2, s4
	v_mov_b32_e32 v3, 0x3000
	global_atomic_add v2, v3, v2, s[2:3] offset:1024 sc0

.LBB0_2464:
	s_andn2_saveexec_b64 s[8:9], s[8:9]
	s_cbranch_execz .LBB0_2484
	s_mov_b64 s[8:9], exec
	s_nop 0
	s_waitcnt lgkmcnt(0)
	s_waitcnt vmcnt(0)
	v_mbcnt_lo_u32_b32 v1, s8, 0
	v_mbcnt_hi_u32_b32 v1, s9, v1
	v_cmp_eq_u32_e32 vcc, 0, v1
	s_and_saveexec_b64 s[10:11], vcc
	s_cbranch_execz .LBB0_2467
	s_bcnt1_i32_b64 s8, s[8:9]
	v_mov_b32_e32 v2, s8
	v_mov_b32_e32 v3, 0x3000
	global_atomic_add v2, v3, v2, s[6:7] offset:1024 sc0

.LBB0_2523:
	v_mbcnt_lo_u32_b32 v138, -1, 0
	v_mbcnt_hi_u32_b32 v138, -1, v138
	s_lshl_b32 s10, s34, 8
	v_and_or_b32 v139, v138, 15, s23
	s_lshl_b32 s11, s31, 8
	s_add_i32 s10, s10, 0xfc000
	s_and_b32 s11, s11, 0x300
	v_lshrrev_b32_e32 v138, 1, v138
	v_and_b32_e32 v138, 0x3ffffff8, v138
	s_or_b32 s11, s11, s24
	v_add_lshl_u32 v139, s10, v139, 12
	s_lshl_b32 s10, s31, 20
	s_and_b32 s10, s10, 0xffc00000
	v_add_lshl_u32 v138, s11, v138, 2
	v_add3_u32 v138, v139, s10, v138
	buffer_store_dwordx4 v[20:23], v138, s[44:47], 0 offen sc1
	buffer_store_dwordx4 v[28:31], v138, s[44:47], 0 offen offset:16 sc1
	buffer_store_dwordx4 v[52:55], v138, s[44:47], 0 offen offset:512 sc1
	buffer_store_dwordx4 v[60:63], v138, s[44:47], 0 offen offset:528 sc1
	v_add_u32_e32 v20, 0x10000, v138
	buffer_store_dwordx4 v[12:15], v20, s[44:47], 0 offen sc1
	buffer_store_dwordx4 v[24:27], v20, s[44:47], 0 offen offset:16 sc1
	buffer_store_dwordx4 v[44:47], v20, s[44:47], 0 offen offset:512 sc1
	buffer_store_dwordx4 v[56:59], v20, s[44:47], 0 offen offset:528 sc1
	v_add_u32_e32 v12, 0x20000, v138
	buffer_store_dwordx4 v[4:7], v12, s[44:47], 0 offen sc1
	buffer_store_dwordx4 v[16:19], v12, s[44:47], 0 offen offset:16 sc1
	buffer_store_dwordx4 v[36:39], v12, s[44:47], 0 offen offset:512 sc1
	buffer_store_dwordx4 v[48:51], v12, s[44:47], 0 offen offset:528 sc1
	v_add_u32_e32 v4, 0x30000, v138
	buffer_store_dwordx4 v[0:3], v4, s[44:47], 0 offen sc1
	buffer_store_dwordx4 v[8:11], v4, s[44:47], 0 offen offset:16 sc1
	buffer_store_dwordx4 v[32:35], v4, s[44:47], 0 offen offset:512 sc1
	buffer_store_dwordx4 v[40:43], v4, s[44:47], 0 offen offset:528 sc1
	v_add_u32_e32 v0, 0x80000, v138
	buffer_store_dwordx4 v[86:89], v0, s[44:47], 0 offen sc1
	buffer_store_dwordx4 v[94:97], v0, s[44:47], 0 offen offset:16 sc1
	buffer_store_dwordx4 v[118:121], v0, s[44:47], 0 offen offset:512 sc1
	buffer_store_dwordx4 v[126:129], v0, s[44:47], 0 offen offset:528 sc1
	v_add_u32_e32 v0, 0x90000, v138
	buffer_store_dwordx4 v[78:81], v0, s[44:47], 0 offen sc1
	buffer_store_dwordx4 v[90:93], v0, s[44:47], 0 offen offset:16 sc1
	buffer_store_dwordx4 v[110:113], v0, s[44:47], 0 offen offset:512 sc1
	buffer_store_dwordx4 v[122:125], v0, s[44:47], 0 offen offset:528 sc1
	v_add_u32_e32 v0, 0xa0000, v138
	buffer_store_dwordx4 v[70:73], v0, s[44:47], 0 offen sc1
	buffer_store_dwordx4 v[82:85], v0, s[44:47], 0 offen offset:16 sc1
	buffer_store_dwordx4 v[102:105], v0, s[44:47], 0 offen offset:512 sc1
	buffer_store_dwordx4 v[114:117], v0, s[44:47], 0 offen offset:528 sc1
	v_add_u32_e32 v0, 0xb0000, v138
	s_and_b64 vcc, exec, s[2:3]
	s_mov_b64 s[2:3], -1
	v_mov_b32_e32 v227, 0x358637bd
	v_mov_b32_e32 v232, 0x41b17218
	v_mov_b32_e32 v233, 0x1000
	v_mov_b64_e32 v[236:237], 0x100
	v_mov_b64_e32 v[250:251], 0xff
	v_mov_b32_e32 v226, 0x80
	buffer_store_dwordx4 v[66:69], v0, s[44:47], 0 offen sc1
	buffer_store_dwordx4 v[74:77], v0, s[44:47], 0 offen offset:16 sc1
	buffer_store_dwordx4 v[98:101], v0, s[44:47], 0 offen offset:512 sc1
	buffer_store_dwordx4 v[106:109], v0, s[44:47], 0 offen offset:528 sc1
	s_cbranch_vccnz .LBB0_2514
	s_andn2_b64 vcc, exec, s[0:1]
	s_cbranch_vccnz .LBB0_2513
	s_barrier
	s_branch .LBB0_2513

.LBB0_2560:
	s_mov_b64 s[4:5], exec
	s_nop 0
	s_waitcnt lgkmcnt(0)
	s_waitcnt vmcnt(0)
	v_mbcnt_lo_u32_b32 v1, s4, 0
	v_mbcnt_hi_u32_b32 v1, s5, v1
	v_cmp_eq_u32_e32 vcc, 0, v1
	s_and_saveexec_b64 s[6:7], vcc
	s_cbranch_execz .LBB0_2562
	s_bcnt1_i32_b64 s4, s[4:5]
	v_mov_b32_e32 v2, s4
	v_mov_b32_e32 v3, 0x3000
	global_atomic_add v2, v3, v2, s[2:3] offset:1024 sc0
